# no entry grid.sync + background buffer_wbl2 from wave 1 of every WG on barrier arrival (pre-flush L2 during arrival skew)
# baseline (speedup 1.0000x reference)
; __device__ __forceinline__ void xcd_barrier(const XcdBarrier& b) {
;     asm volatile("s_waitcnt vmcnt(0)" ::: "memory");
;     __syncthreads();
;     if (threadIdx.x == 0) {
; __global__ void __launch_bounds__(512, 2) mega_fwd(Args args) {
;     ...
;         for (int rep_ = 0; rep_ < ((REPMASK & 64) ? 2 : 1); ++rep_)
;         if (ph + 1 < args.ph_hi) {
;             {
;                 xcd_barrier(xbar);
;             }
;         }
;     }
.LBB0_519:
	v_readlane_b32 s12, v253, 4
	v_readlane_b32 s13, v253, 5
	s_add_i32 s12, s12, 1
	v_writelane_b32 v253, s12, 4
	s_cmp_ge_i32 s12, s13
	s_nop 0
	v_writelane_b32 v253, s13, 5
	s_mov_b64 s[12:13], -1
	s_cbranch_scc1 .LBB0_19
	s_waitcnt vmcnt(0)
	s_waitcnt vmcnt(0) lgkmcnt(0)
	s_barrier
	v_readlane_b32 s98, v252, 47
	s_nop 1
	s_cmp_lg_u32 s98, 1
	s_cbranch_scc1 .Lxb_nowb
	buffer_wbl2 sc1
.Lxb_nowb:
	s_mov_b64 s[12:13], exec
	v_readlane_b32 s16, v253, 2
	v_readlane_b32 s17, v253, 3
	s_and_b64 s[16:17], s[12:13], s[16:17]
	s_mov_b64 exec, s[16:17]
	s_cbranch_execz .LBB0_18
	s_waitcnt vmcnt(0) expcnt(0) lgkmcnt(0)
	ds_read_b32 v2, v220
	ds_read_b32 v0, v221
	s_waitcnt lgkmcnt(1)
	v_cmp_ne_u32_e32 vcc, 0, v2
	s_cbranch_vccnz .LBB0_536
	s_mov_b32 s0, 1
	s_branch .LBB0_524
